# v59 with the early full vmcnt(0) of the first attention unit's start-up dropped (the wait in front of the first MFMA remains), so index arithmetic overlaps the initial loads
# speedup vs baseline: 1.0004x; 1.0004x over previous
; #define LAS __attribute__((address_space(3)))
; template <bool DIAG, int QT0>
; __device__ __forceinline__ void attn_group(const bf16x8 (&Kf)[2][2], const bf16x8 (&Vf)[4], const bf16x8 (&Qf)[4][2], f32x4 (&ot)[4][4], float (&carry)[4], int qb, int key0, int fr, int fq) {
;     ...
;         f32x4 s0 = (f32x4){0.f, 0.f, 0.f, 0.f}, s1 = (f32x4){0.f, 0.f, 0.f, 0.f};
; #pragma unroll
; __device__ __forceinline__ void attn_unit(const bf16* __restrict__ U, const bf16* __restrict__ VT, bf16* __restrict__ Y, int b, int qb, LAS float* red, int wave, int lane) {
;     const int h = wave, fr = lane & 15, fq = lane >> 4;
;     const size_t rowq = (size_t)b * SEQ + (size_t)qb * 64;
;     bf16x8 Qf[4][2];
; #pragma unroll
;     for (int qt = 0; qt < 4; ++qt)
; #pragma unroll
;         for (int ks = 0; ks < 2; ++ks) Qf[qt][ks] = *(const bf16x8*)(U + (rowq + 16 * qt + fr) * NU + 1024 + h * 64 + 32 * ks + 8 * fq);
;     f32x4 ot[4][4];
; #pragma unroll
;     for (int dt = 0; dt < 4; ++dt)
; #pragma unroll
;         for (int qt = 0; qt < 4; ++qt) ot[dt][qt] = (f32x4){0.f, 0.f, 0.f, 0.f};
;     float carry[4] = {1.f, 1.f, 1.f, 1.f};
;     const bf16* Kbase = U + ((size_t)b * SEQ + 8 * (fr >> 2) + (fr & 3)) * NU + 1536 + h * 64 + 8 * fq;
;     const bf16* Vbase = VT + ((size_t)(b * 8 + h) * 64 + fr) * SEQ + 8 * fq;
;     bf16x8 Kn[2][2], Vn[4], Kf[2][2], Vf[4];
;     auto fetch = [&](int kgn) { const int keyn = (kgn > 0 ? kgn : 0) * 32;
; #pragma unroll
;         for (int sub = 0; sub < 2; ++sub)
; #pragma unroll
;             for (int ks = 0; ks < 2; ++ks) Kn[sub][ks] = *(const bf16x8*)(Kbase + (size_t)(keyn + 4 * sub) * NU + 32 * ks);
; #pragma unroll
;         for (int dt = 0; dt < 4; ++dt) Vn[dt] = *(const bf16x8*)(Vbase + (size_t)dt * 16 * SEQ + keyn); };
;     auto take = [&]() {
; #pragma unroll
;         for (int sub = 0; sub < 2; ++sub)
; #pragma unroll
;             for (int ks = 0; ks < 2; ++ks) Kf[sub][ks] = Kn[sub][ks];
; #pragma unroll
;         for (int dt = 0; dt < 4; ++dt) Vf[dt] = Vn[dt]; };
;     fetch(2 * qb + 1);
;     take(); fetch(2 * qb);     attn_group<true, 2>(Kf, Vf, Qf, ot, carry, qb, (2 * qb + 1) * 32, fr, fq);
;     take(); fetch(2 * qb - 1); attn_group<true, 0>(Kf, Vf, Qf, ot, carry, qb, (2 * qb) * 32, fr, fq);
.LBB0_219:
	s_ashr_i32 s0, s18, 31
	s_lshr_b32 s0, s0, 26
	s_add_i32 s0, s18, s0
	s_ashr_i32 s12, s0, 6
	s_andn2_b32 s0, s0, 63
	s_sub_i32 s10, s18, s0
	s_lshl_b32 s90, s10, 1
	s_ashr_i32 s13, s12, 31
	s_ashr_i32 s91, s90, 31
	s_lshl_b64 s[88:89], s[12:13], 13
	s_lshl_b64 s[0:1], s[90:91], 6
	s_add_u32 s11, s0, s88
	s_addc_u32 s15, s1, s89
	v_mov_b32_e32 v1, s15
	v_or_b32_e32 v0, s11, v182
	s_lshl_b32 s14, s10, 2
	v_lshlrev_b64 v[0:1], 12, v[0:1]
	s_or_b32 s16, s14, 1
	v_lshl_add_u64 v[4:5], v[190:191], 0, v[0:1]
	v_mov_b32_e32 v1, s89
	v_or_b32_e32 v0, s88, v186
	s_max_i32 s17, s16, 0
	v_lshlrev_b64 v[0:1], 12, v[0:1]
	s_lshl_b32 s58, s17, 5
	v_lshl_add_u64 v[192:193], v[190:191], 0, v[0:1]
	s_lshl_b64 s[0:1], s[58:59], 12
	v_lshl_add_u64 v[6:7], v[192:193], 0, s[0:1]
	global_load_dwordx4 v[84:87], v[6:7], off offset:3072
	global_load_dwordx4 v[0:3], v[4:5], off offset:2048
	s_or_b32 s58, s58, 4
	s_lshl_b64 s[0:1], s[58:59], 12
	v_lshl_add_u64 v[8:9], v[192:193], 0, s[0:1]
	global_load_dwordx4 v[92:95], v[8:9], off offset:3072
	global_load_dwordx4 v[88:91], v[6:7], off offset:3136
	s_nop 0
	global_load_dwordx4 v[4:7], v[4:5], off offset:2112
	s_nop 0
	global_load_dwordx4 v[72:75], v[8:9], off offset:3136
	v_or_b32_e32 v202, s11, v172
	v_or_b32_e32 v8, s11, v180
	v_or_b32_e32 v10, s11, v184
	v_mov_b32_e32 v203, s15
	v_mov_b32_e32 v9, s15
	v_mov_b32_e32 v11, s15
	v_lshlrev_b64 v[12:13], 12, v[202:203]
	v_lshlrev_b64 v[8:9], 12, v[8:9]
	v_lshlrev_b64 v[10:11], 12, v[10:11]
	v_lshl_add_u64 v[12:13], v[190:191], 0, v[12:13]
	v_lshl_add_u64 v[20:21], v[190:191], 0, v[8:9]
	v_lshl_add_u64 v[28:29], v[190:191], 0, v[10:11]
	global_load_dwordx4 v[8:11], v[12:13], off offset:2048
	s_nop 0
	global_load_dwordx4 v[12:15], v[12:13], off offset:2112
	s_nop 0
	global_load_dwordx4 v[16:19], v[20:21], off offset:2048
	s_nop 0
	global_load_dwordx4 v[20:23], v[20:21], off offset:2112
	s_nop 0
	global_load_dwordx4 v[24:27], v[28:29], off offset:2048
	s_nop 0
	global_load_dwordx4 v[28:31], v[28:29], off offset:2112
	s_lshl_b32 s0, s12, 3
	s_add_i32 s0, s0, s74
	s_ashr_i32 s1, s0, 31
	s_lshl_b64 s[0:1], s[0:1], 20
	v_lshl_add_u64 v[194:195], v[188:189], 0, s[0:1]
	s_lshl_b32 s58, s17, 6
	v_lshl_add_u64 v[196:197], v[194:195], 0, s[62:63]
	v_lshl_add_u64 v[198:199], v[194:195], 0, s[64:65]
	v_lshl_add_u64 v[200:201], v[194:195], 0, s[66:67]
	v_lshl_add_u64 v[36:37], v[194:195], 0, s[58:59]
	v_lshl_add_u64 v[38:39], v[196:197], 0, s[58:59]
	v_lshl_add_u64 v[40:41], v[198:199], 0, s[58:59]
	v_lshl_add_u64 v[42:43], v[200:201], 0, s[58:59]
	global_load_dwordx4 v[68:71], v[36:37], off
	global_load_dwordx4 v[64:67], v[38:39], off
	global_load_dwordx4 v[80:83], v[40:41], off
	global_load_dwordx4 v[76:79], v[42:43], off
	s_max_i32 s15, s14, 0
	s_lshl_b32 s58, s15, 5
	s_lshl_b64 s[0:1], s[58:59], 12
	v_lshl_add_u64 v[40:41], v[192:193], 0, s[0:1]
	global_load_dwordx4 v[52:55], v[40:41], off offset:3072
	global_load_dwordx4 v[44:47], v[40:41], off offset:3136
	s_lshl_b32 s13, s10, 7
	v_or_b32_e32 v98, s13, v172
	v_lshl_or_b32 v99, s16, 5, v176
	v_or_b32_e32 v96, 32, v98
	v_cmp_lt_i32_e32 vcc, v99, v96
	v_or_b32_e32 v104, 3, v99
	v_or_b32_e32 v106, 4, v99
	v_or_b32_e32 v108, 5, v99
	v_or_b32_e32 v110, 6, v99
	v_or_b32_e32 v112, 7, v99
	v_or_b32_e32 v101, 2, v99
	v_or_b32_e32 v100, 1, v99
	v_cmp_lt_i32_e64 s[10:11], v101, v96
	v_cmp_lt_i32_e64 s[0:1], v100, v96
	s_or_b32 s58, s58, 4
	s_lshl_b64 s[16:17], s[58:59], 12
	s_lshl_b32 s58, s15, 6
	s_waitcnt vmcnt(0)
	v_mfma_f32_16x16x32_bf16 v[32:35], v[84:87], v[0:3], 0
	v_mfma_f32_16x16x32_bf16 v[32:35], v[88:91], v[4:7], v[32:35]
	v_mfma_f32_16x16x32_bf16 v[36:39], v[92:95], v[0:3], 0
	v_mfma_f32_16x16x32_bf16 v[36:39], v[72:75], v[4:7], v[36:39]
	s_nop 5
	v_mul_f32_e32 v32, 0xbe38aa3b, v32
	v_min_f32_e32 v32, 0x42e60000, v32
	v_exp_f32_e32 v32, v32
	v_mul_f32_e32 v35, 0xbe38aa3b, v35
	v_min_f32_e32 v35, 0x42e60000, v35
	v_exp_f32_e32 v35, v35
	v_add_f32_e32 v40, 1.0, v32
	v_rcp_f32_e32 v40, v40
	v_mul_f32_e32 v36, 0xbe38aa3b, v36
	v_add_f32_e32 v43, 1.0, v35
	v_min_f32_e32 v36, 0x42e60000, v36
	v_cndmask_b32_e32 v97, 0, v40, vcc
	v_mul_f32_e32 v32, v32, v40
	v_rcp_f32_e32 v40, v43
	v_exp_f32_e32 v36, v36
	v_cndmask_b32_e32 v32, 1.0, v32, vcc
	v_cmp_lt_i32_e32 vcc, v104, v96
	v_mul_f32_e32 v37, 0xbe38aa3b, v37
	v_mul_f32_e32 v35, v35, v40
	v_cndmask_b32_e32 v105, 0, v40, vcc
	v_add_f32_e32 v40, 1.0, v36
	v_min_f32_e32 v37, 0x42e60000, v37
	v_rcp_f32_e32 v40, v40
	v_exp_f32_e32 v37, v37
	v_cndmask_b32_e32 v35, 1.0, v35, vcc
	v_cmp_lt_i32_e32 vcc, v106, v96
	v_mul_f32_e32 v38, 0xbe38aa3b, v38
	v_mul_f32_e32 v36, v36, v40
	v_cndmask_b32_e32 v107, 0, v40, vcc
	v_add_f32_e32 v40, 1.0, v37
	v_min_f32_e32 v38, 0x42e60000, v38
	v_rcp_f32_e32 v40, v40
	v_exp_f32_e32 v38, v38
	v_cndmask_b32_e32 v36, 1.0, v36, vcc
	v_cmp_lt_i32_e32 vcc, v108, v96
	v_mul_f32_e32 v39, 0xbe38aa3b, v39
	v_mul_f32_e32 v37, v37, v40
	v_cndmask_b32_e32 v109, 0, v40, vcc
	v_add_f32_e32 v40, 1.0, v38
	v_min_f32_e32 v39, 0x42e60000, v39
	v_rcp_f32_e32 v40, v40
	v_exp_f32_e32 v39, v39
	v_mul_f32_e32 v34, 0xbe38aa3b, v34
	v_mul_f32_e32 v33, 0xbe38aa3b, v33
	v_min_f32_e32 v34, 0x42e60000, v34
	v_cndmask_b32_e32 v37, 1.0, v37, vcc
	v_cmp_lt_i32_e32 vcc, v110, v96
	v_min_f32_e32 v33, 0x42e60000, v33
	v_exp_f32_e32 v34, v34
	v_cndmask_b32_e32 v111, 0, v40, vcc
	v_mul_f32_e32 v38, v38, v40
	v_add_f32_e32 v40, 1.0, v39
	v_exp_f32_e32 v33, v33
	v_rcp_f32_e32 v40, v40
	v_add_f32_e32 v42, 1.0, v34
	v_rcp_f32_e32 v42, v42
	v_add_f32_e32 v41, 1.0, v33
	v_cndmask_b32_e32 v38, 1.0, v38, vcc
	v_cmp_lt_i32_e32 vcc, v112, v96
	v_mul_f32_e32 v39, v39, v40
	v_rcp_f32_e32 v41, v41
	v_cndmask_b32_e32 v114, 1.0, v39, vcc
	v_mul_f32_e32 v115, v114, v38
	v_mul_f32_e32 v116, v37, v115
	v_mul_f32_e32 v34, v34, v42
	v_mul_f32_e32 v117, v36, v116
	v_mul_f32_e32 v33, v33, v41
	v_cndmask_b32_e64 v34, 1.0, v34, s[10:11]
	v_mul_f32_e32 v118, v35, v117
	v_cndmask_b32_e64 v33, 1.0, v33, s[0:1]
	v_mul_f32_e32 v119, v34, v118
	v_mul_f32_e32 v120, v33, v119
	v_mul_f32_e32 v34, v32, v120
	ds_bpermute_b32 v35, v175, v34
	v_lshl_add_u64 v[32:33], v[192:193], 0, s[16:17]
	global_load_dwordx4 v[60:63], v[32:33], off offset:3072
	global_load_dwordx4 v[56:59], v[32:33], off offset:3136
	v_mfma_f32_16x16x32_bf16 v[84:87], v[84:87], v[24:27], 0
	v_cndmask_b32_e64 v102, 0, v41, s[0:1]
	s_waitcnt lgkmcnt(0)
; __device__ __forceinline__ unsigned pk2(float lo, float hi) { return pg8::cvt_pk_bf16(lo, hi); }
; template <bool DIAG, int QT0>
; __device__ __forceinline__ void attn_group(const bf16x8 (&Kf)[2][2], const bf16x8 (&Vf)[4], const bf16x8 (&Qf)[4][2], f32x4 (&ot)[4][4], float (&carry)[4], int qb, int key0, int fr, int fq) {
;     ...
;         float ex[8], run = 1.f;
; #pragma unroll
;         for (int e = 7; e >= 0; --e) { ex[e] = run; run *= om[e]; }
;         const float T = run;
;         const float t1 = __shfl_down(T, 16); const float I1 = T * (fq < 3 ? t1 : 1.f);
;         const float t2 = __shfl_down(I1, 32); const float I2 = I1 * (fq < 2 ? t2 : 1.f);
;         const float xs = __shfl_down(I2, 16); const float X = (fq < 3 ? xs : 1.f);
;         const float TT = __shfl(I2, fr);
;         const float base = carry[qt] * X;
;         float p[8];
; #pragma unroll
;         for (int e = 0; e < 8; ++e) p[e] = be[e] * (base * ex[e]);
;         carry[qt] *= TT;
;         v4u pw; pw.x = pk2(p[0], p[1]); pw.y = pk2(p[2], p[3]); pw.z = pk2(p[4], p[5]); pw.w = pk2(p[6], p[7]);
;         Pf[qt] = __builtin_bit_cast(bf16x8, pw);
;     }
; #pragma unroll
;     for (int dt = 0; dt < 4; ++dt)
; #pragma unroll
;         for (int qt = QT0; qt < 4; ++qt) if (live[qt]) ot[dt][qt] = __builtin_amdgcn_mfma_f32_16x16x32_bf16(Vf[dt], Pf[qt], ot[dt][qt], 0, 0, 0);
	v_cndmask_b32_e64 v32, v35, 1.0, s[2:3]
	v_mul_f32_e32 v48, v32, v34
	ds_bpermute_b32 v49, v181, v48
	v_mfma_f32_16x16x32_bf16 v[84:87], v[88:91], v[28:31], v[84:87]
	v_lshl_add_u64 v[32:33], v[194:195], 0, s[58:59]
	v_cndmask_b32_e64 v103, 0, v42, s[10:11]
	v_cndmask_b32_e32 v113, 0, v40, vcc
	v_lshl_add_u64 v[34:35], v[196:197], 0, s[58:59]
	global_load_dwordx4 v[40:43], v[32:33], off
	global_load_dwordx4 v[36:39], v[34:35], off
	s_waitcnt lgkmcnt(0)
	v_cndmask_b32_e64 v32, 1.0, v49, s[4:5]
	v_mul_f32_e32 v121, v32, v48
	ds_bpermute_b32 v122, v175, v121
	v_mul_f32_e32 v84, 0xbe38aa3b, v84
	v_min_f32_e32 v84, 0x42e60000, v84
	v_exp_f32_e32 v84, v84
	v_mul_f32_e32 v85, 0xbe38aa3b, v85
	s_waitcnt lgkmcnt(0)
	v_cndmask_b32_e64 v122, v122, 1.0, s[2:3]
	v_mul_f32_e32 v120, v122, v120
	v_add_f32_e32 v89, 1.0, v84
	v_min_f32_e32 v85, 0x42e60000, v85
	v_mul_f32_e32 v120, v97, v120
	v_mul_f32_e32 v97, v122, v119
	v_rcp_f32_e32 v89, v89
	v_exp_f32_e32 v85, v85
	v_mul_f32_e32 v102, v102, v97
	v_mul_f32_e32 v97, v122, v118
	v_mul_f32_e32 v103, v103, v97
	v_or_b32_e32 v97, 48, v98
	v_cmp_lt_i32_e32 vcc, v99, v97
	v_mul_f32_e32 v86, 0xbe38aa3b, v86
	v_mul_f32_e32 v84, v84, v89
	v_cndmask_b32_e32 v90, 0, v89, vcc
	v_add_f32_e32 v89, 1.0, v85
	v_min_f32_e32 v86, 0x42e60000, v86
	v_mfma_f32_16x16x32_bf16 v[92:95], v[92:95], v[24:27], 0
	v_rcp_f32_e32 v89, v89
	v_exp_f32_e32 v86, v86
	v_cndmask_b32_e32 v84, 1.0, v84, vcc
	v_cmp_lt_i32_e32 vcc, v100, v97
	v_mul_f32_e32 v87, 0xbe38aa3b, v87
	v_mfma_f32_16x16x32_bf16 v[72:75], v[72:75], v[28:31], v[92:95]
	v_cndmask_b32_e32 v91, 0, v89, vcc
	v_mul_f32_e32 v85, v85, v89
	v_add_f32_e32 v89, 1.0, v86
	v_min_f32_e32 v87, 0x42e60000, v87
	v_rcp_f32_e32 v89, v89
	v_exp_f32_e32 v87, v87
	v_cndmask_b32_e32 v85, 1.0, v85, vcc
	v_cmp_lt_i32_e32 vcc, v101, v97
	v_mul_f32_e32 v72, 0xbe38aa3b, v72
	v_mul_f32_e32 v86, v86, v89
	v_cndmask_b32_e32 v92, 0, v89, vcc
	v_add_f32_e32 v89, 1.0, v87
	v_min_f32_e32 v72, 0x42e60000, v72
	v_rcp_f32_e32 v89, v89
	v_exp_f32_e32 v72, v72
	v_cndmask_b32_e32 v86, 1.0, v86, vcc
	v_cmp_lt_i32_e32 vcc, v104, v97
	v_mul_f32_e32 v73, 0xbe38aa3b, v73
	v_mul_f32_e32 v87, v87, v89
	v_cndmask_b32_e32 v93, 0, v89, vcc
	v_add_f32_e32 v89, 1.0, v72
	v_min_f32_e32 v73, 0x42e60000, v73
	v_rcp_f32_e32 v89, v89
	v_exp_f32_e32 v73, v73
	v_cndmask_b32_e32 v87, 1.0, v87, vcc
	v_cmp_lt_i32_e32 vcc, v106, v97
	v_mul_f32_e32 v74, 0xbe38aa3b, v74
	v_mul_f32_e32 v72, v72, v89
	v_cndmask_b32_e32 v94, 0, v89, vcc
	v_add_f32_e32 v89, 1.0, v73
	v_min_f32_e32 v74, 0x42e60000, v74
	v_mul_f32_e32 v75, 0xbe38aa3b, v75
	v_rcp_f32_e32 v89, v89
	v_exp_f32_e32 v74, v74
	v_min_f32_e32 v75, 0x42e60000, v75
	v_exp_f32_e32 v75, v75
	v_cndmask_b32_e32 v72, 1.0, v72, vcc
	v_cmp_lt_i32_e32 vcc, v108, v97
	v_mul_f32_e32 v73, v73, v89
	v_add_f32_e32 v100, 1.0, v75
	v_cndmask_b32_e32 v95, 0, v89, vcc
	v_add_f32_e32 v89, 1.0, v74
	v_rcp_f32_e32 v89, v89
	v_rcp_f32_e32 v100, v100
	v_cndmask_b32_e32 v73, 1.0, v73, vcc
	v_cmp_lt_i32_e32 vcc, v110, v97
	v_mul_f32_e32 v74, v74, v89
	v_mul_f32_e32 v75, v75, v100
	v_cndmask_b32_e32 v99, 0, v89, vcc
	v_cndmask_b32_e32 v74, 1.0, v74, vcc
	v_cmp_lt_i32_e32 vcc, v112, v97
	v_mul_f32_e32 v88, v122, v117
	v_lshl_add_u64 v[32:33], v[198:199], 0, s[58:59]
	v_cndmask_b32_e32 v75, 1.0, v75, vcc
	v_mul_f32_e32 v74, v75, v74
	v_mul_f32_e32 v73, v73, v74
	v_mul_f32_e32 v72, v72, v73
	v_cndmask_b32_e32 v89, 0, v100, vcc
	v_mul_f32_e32 v100, v87, v72
	v_mul_f32_e32 v101, v86, v100
	v_mul_f32_e32 v104, v85, v101
	v_mul_f32_e32 v84, v84, v104
	ds_bpermute_b32 v85, v175, v84
	v_mul_f32_e32 v87, v122, v116
	v_mul_f32_e32 v87, v107, v87
	v_mul_f32_e32 v86, v105, v88
	v_mul_f32_e32 v88, v122, v115
	s_waitcnt lgkmcnt(0)
	v_cndmask_b32_e64 v85, v85, 1.0, s[2:3]
	v_mul_f32_e32 v84, v85, v84
	ds_bpermute_b32 v85, v181, v84
	v_lshl_add_u64 v[34:35], v[200:201], 0, s[58:59]
	v_mul_f32_e32 v88, v109, v88
	global_load_dwordx4 v[48:51], v[32:33], off
	s_nop 0
	global_load_dwordx4 v[32:35], v[34:35], off
	v_mul_f32_e32 v105, v122, v114
	s_waitcnt lgkmcnt(0)
	v_cndmask_b32_e64 v85, 1.0, v85, s[4:5]
	v_mul_f32_e32 v108, v85, v84
	ds_bpermute_b32 v107, v175, v108
	v_cvt_pk_bf16_f32 v84, v120, v102
	v_cvt_pk_bf16_f32 v85, v103, v86
	v_cvt_pk_bf16_f32 v86, v87, v88
	v_mul_f32_e32 v105, v111, v105
	s_waitcnt lgkmcnt(0)
	v_cndmask_b32_e64 v88, v107, 1.0, s[2:3]
	v_mul_f32_e32 v72, v88, v72
	v_mul_f32_e32 v93, v93, v72
	v_mul_f32_e32 v72, v88, v73
	v_mul_f32_e32 v94, v94, v72
	v_mul_f32_e32 v72, v88, v74
	v_mul_f32_e32 v106, v122, v113
	v_mul_f32_e32 v102, v88, v104
	v_mul_f32_e32 v101, v88, v101
	v_mul_f32_e32 v100, v88, v100
	v_mul_f32_e32 v95, v95, v72
	v_mul_f32_e32 v72, v88, v75
	v_cvt_pk_bf16_f32 v87, v105, v106
	v_mul_f32_e32 v90, v90, v102
	v_mul_f32_e32 v91, v91, v101
	v_mul_f32_e32 v92, v92, v100
	v_mul_f32_e32 v99, v99, v72
	v_mul_f32_e32 v88, v88, v89
	v_cvt_pk_bf16_f32 v104, v90, v91
	v_cvt_pk_bf16_f32 v105, v92, v93
	v_cvt_pk_bf16_f32 v106, v94, v95
	v_cvt_pk_bf16_f32 v107, v99, v88
	v_mfma_f32_16x16x32_bf16 v[132:135], v[76:79], v[84:87], 0
	s_add_i32 s0, s14, -1
	s_max_i32 s10, s0, 0
	s_lshl_b32 s58, s10, 5
	v_mfma_f32_16x16x32_bf16 v[128:131], v[76:79], v[104:107], 0
	s_lshl_b64 s[0:1], s[58:59], 12
	s_or_b32 s58, s58, 4
	ds_bpermute_b32 v140, v183, v121
	v_mfma_f32_16x16x32_bf16 v[76:79], v[52:55], v[8:11], 0
	ds_bpermute_b32 v143, v183, v108
	v_mfma_f32_16x16x32_bf16 v[76:79], v[44:47], v[12:15], v[76:79]
	v_mfma_f32_16x16x32_bf16 v[72:75], v[68:71], v[84:87], 0
	v_mfma_f32_16x16x32_bf16 v[100:103], v[68:71], v[104:107], 0
	s_nop 5
	v_mul_f32_e32 v76, 0xbe38aa3b, v76
	v_min_f32_e32 v76, 0x42e60000, v76
	v_mul_f32_e32 v77, 0xbe38aa3b, v77
	v_mfma_f32_16x16x32_bf16 v[68:71], v[64:67], v[84:87], 0
	v_min_f32_e32 v77, 0x42e60000, v77
	v_mul_f32_e32 v78, 0xbe38aa3b, v78
	v_min_f32_e32 v78, 0x42e60000, v78
	v_mfma_f32_16x16x32_bf16 v[92:95], v[64:67], v[104:107], 0
	v_mul_f32_e32 v79, 0xbe38aa3b, v79
	v_min_f32_e32 v79, 0x42e60000, v79
	v_mfma_f32_16x16x32_bf16 v[64:67], v[80:83], v[84:87], 0
	v_exp_f32_e32 v86, v76
	v_or_b32_e32 v76, s13, v176
	v_or_b32_e32 v154, 4, v76
	v_mfma_f32_16x16x32_bf16 v[88:91], v[80:83], v[104:107], 0
	v_add_f32_e32 v87, 1.0, v86
	v_rcp_f32_e32 v99, v87
	v_exp_f32_e32 v87, v77
	v_lshl_add_u64 v[80:81], v[192:193], 0, s[0:1]
	v_exp_f32_e32 v105, v78
	v_mul_f32_e32 v77, v86, v99
	v_cndmask_b32_e64 v86, 1.0, v77, s[6:7]
	v_add_f32_e32 v77, 1.0, v87
	v_rcp_f32_e32 v104, v77
	global_load_dwordx4 v[116:119], v[80:81], off offset:3072
	global_load_dwordx4 v[112:115], v[80:81], off offset:3136
	s_waitcnt vmcnt(7)
; __device__ __forceinline__ unsigned pk2(float lo, float hi) { return pg8::cvt_pk_bf16(lo, hi); }
; template <bool DIAG, int QT0>
; __device__ __forceinline__ void attn_group(const bf16x8 (&Kf)[2][2], const bf16x8 (&Vf)[4], const bf16x8 (&Qf)[4][2], f32x4 (&ot)[4][4], float (&carry)[4], int qb, int key0, int fr, int fq) {
;     ...
;         f32x4 s0 = (f32x4){0.f, 0.f, 0.f, 0.f}, s1 = (f32x4){0.f, 0.f, 0.f, 0.f};
; #pragma unroll
;         for (int ks = 0; ks < 2; ++ks) { s0 = __builtin_amdgcn_mfma_f32_16x16x32_bf16(Kf[0][ks], Qf[qt][ks], s0, 0, 0, 0); s1 = __builtin_amdgcn_mfma_f32_16x16x32_bf16(Kf[1][ks], Qf[qt][ks], s1, 0, 0, 0); }
;         const int qpos = qb * 64 + 16 * qt + fr, kpos0 = key0 + 8 * fq;
;         float be[8], om[8];
; #pragma unroll
;         for (int e = 0; e < 8; ++e) { const float s = (e < 4 ? s0[e & 3] : s1[e & 3]);
;             const float ez = __builtin_amdgcn_exp2f(fminf(s * (-0.125f * 1.4426950408889634f), 115.0f));
;             const float bt = __builtin_amdgcn_rcpf(1.0f + ez);
;             const bool valid = !DIAG || (kpos0 + e < qpos);
;             be[e] = valid ? bt : 0.f;
;             om[e] = valid ? ez * bt : 1.f; }
;         float ex[8], run = 1.f;
; #pragma unroll
;         for (int e = 7; e >= 0; --e) { ex[e] = run; run *= om[e]; }
;         const float T = run;
;         const float t1 = __shfl_down(T, 16); const float I1 = T * (fq < 3 ? t1 : 1.f);
;         const float t2 = __shfl_down(I1, 32); const float I2 = I1 * (fq < 2 ? t2 : 1.f);
;         const float xs = __shfl_down(I2, 16); const float X = (fq < 3 ? xs : 1.f);
;         const float TT = __shfl(I2, fr);
;         const float base = carry[qt] * X;
;         float p[8];
; #pragma unroll
;         for (int e = 0; e < 8; ++e) p[e] = be[e] * (base * ex[e]);
;         carry[qt] *= TT;
;         v4u pw; pw.x = pk2(p[0], p[1]); pw.y = pk2(p[2], p[3]); pw.z = pk2(p[4], p[5]); pw.w = pk2(p[6], p[7]);
;         Pf[qt] = __builtin_bit_cast(bf16x8, pw);
	v_mfma_f32_16x16x32_bf16 v[80:83], v[60:63], v[8:11], 0
	v_or_b32_e32 v77, 1, v76
	v_cmp_lt_i32_e32 vcc, v77, v98
	v_mul_f32_e32 v78, v87, v104
	s_waitcnt vmcnt(6)
	v_mfma_f32_16x16x32_bf16 v[80:83], v[56:59], v[12:15], v[80:83]
	v_cndmask_b32_e32 v87, 1.0, v78, vcc
	v_add_f32_e32 v78, 1.0, v105
	v_cndmask_b32_e32 v141, 0, v104, vcc
	v_rcp_f32_e32 v104, v78
	v_exp_f32_e32 v106, v79
	v_or_b32_e32 v78, 2, v76
	v_cmp_lt_i32_e32 vcc, v78, v98
	v_mul_f32_e32 v79, v105, v104
	v_mul_f32_e32 v80, 0xbe38aa3b, v80
	v_cndmask_b32_e32 v142, 0, v104, vcc
	v_cndmask_b32_e32 v104, 1.0, v79, vcc
	v_add_f32_e32 v79, 1.0, v106
	v_min_f32_e32 v80, 0x42e60000, v80
	v_rcp_f32_e32 v105, v79
	v_exp_f32_e32 v80, v80
	v_or_b32_e32 v79, 3, v76
	v_cmp_lt_i32_e32 vcc, v79, v98
	v_mul_f32_e32 v81, 0xbe38aa3b, v81
	v_min_f32_e32 v81, 0x42e60000, v81
	v_cndmask_b32_e32 v145, 0, v105, vcc
	v_mul_f32_e32 v105, v106, v105
	v_add_f32_e32 v106, 1.0, v80
	v_rcp_f32_e32 v106, v106
	v_exp_f32_e32 v81, v81
	v_cndmask_b32_e32 v105, 1.0, v105, vcc
	v_cmp_lt_i32_e32 vcc, v154, v98
	v_mul_f32_e32 v82, 0xbe38aa3b, v82
	v_mul_f32_e32 v80, v80, v106
	v_cndmask_b32_e32 v150, 0, v106, vcc
	v_add_f32_e32 v106, 1.0, v81
	v_min_f32_e32 v82, 0x42e60000, v82
	v_rcp_f32_e32 v106, v106
	v_exp_f32_e32 v82, v82
	v_or_b32_e32 v155, 5, v76
	v_cndmask_b32_e32 v80, 1.0, v80, vcc
	v_cmp_lt_i32_e32 vcc, v155, v98
	v_mul_f32_e32 v83, 0xbe38aa3b, v83
	v_mul_f32_e32 v81, v81, v106
	v_cndmask_b32_e32 v151, 0, v106, vcc
	v_add_f32_e32 v106, 1.0, v82
	v_min_f32_e32 v83, 0x42e60000, v83
	v_rcp_f32_e32 v106, v106
	v_exp_f32_e32 v83, v83
	v_or_b32_e32 v156, 6, v76
	v_cndmask_b32_e32 v81, 1.0, v81, vcc
	v_cmp_lt_i32_e32 vcc, v156, v98
	v_mul_f32_e32 v82, v82, v106
	v_or_b32_e32 v157, 7, v76
	v_cndmask_b32_e32 v152, 0, v106, vcc
	v_add_f32_e32 v106, 1.0, v83
	v_rcp_f32_e32 v106, v106
	v_cndmask_b32_e32 v82, 1.0, v82, vcc
	v_cmp_lt_i32_e32 vcc, v157, v98
	s_lshl_b64 s[0:1], s[58:59], 12
	v_mul_f32_e32 v83, v83, v106
	v_cndmask_b32_e32 v158, 1.0, v83, vcc
	v_mul_f32_e32 v159, v158, v82
	v_mul_f32_e32 v160, v81, v159
	v_mul_f32_e32 v161, v80, v160
	v_mul_f32_e32 v162, v105, v161
	v_mul_f32_e32 v146, v104, v162
	v_mul_f32_e32 v136, v87, v146
	v_mul_f32_e32 v82, v86, v136
	ds_bpermute_b32 v83, v175, v82
	v_lshl_add_u64 v[84:85], v[192:193], 0, s[0:1]
	global_load_dwordx4 v[124:127], v[84:85], off offset:3072
	global_load_dwordx4 v[120:123], v[84:85], off offset:3136
	s_lshl_b32 s58, s10, 6
	v_lshl_add_u64 v[80:81], v[194:195], 0, s[58:59]
	s_waitcnt lgkmcnt(0)
	v_cndmask_b32_e64 v83, v83, 1.0, s[2:3]
	v_mul_f32_e32 v84, v83, v82
	ds_bpermute_b32 v85, v181, v84
	v_lshl_add_u64 v[82:83], v[196:197], 0, s[58:59]
	v_cndmask_b32_e32 v153, 0, v106, vcc
	global_load_dwordx4 v[108:111], v[80:81], off
	global_load_dwordx4 v[104:107], v[82:83], off
	v_or_b32_e32 v98, 16, v98
	s_waitcnt lgkmcnt(0)
	v_cndmask_b32_e64 v82, 1.0, v85, s[4:5]
	v_mul_f32_e32 v144, v82, v84
	ds_bpermute_b32 v137, v175, v144
	v_cmp_lt_i32_e32 vcc, v76, v98
	v_cndmask_b32_e64 v99, 0, v99, s[6:7]
	v_lshl_add_u64 v[80:81], v[198:199], 0, s[58:59]
	v_lshl_add_u64 v[82:83], v[200:201], 0, s[58:59]
	s_waitcnt lgkmcnt(0)
	v_cndmask_b32_e64 v163, v137, 1.0, s[2:3]
	v_mul_f32_e32 v147, v163, v136
	v_mfma_f32_16x16x32_bf16 v[136:139], v[52:55], v[16:19], 0
	v_mul_f32_e32 v161, v163, v161
	v_mul_f32_e32 v145, v145, v161
	v_mul_f32_e32 v162, v163, v162
	v_mfma_f32_16x16x32_bf16 v[136:139], v[44:47], v[20:23], v[136:139]
	v_mul_f32_e32 v146, v163, v146
	v_mul_f32_e32 v142, v142, v162
	v_mul_f32_e32 v99, v99, v147
	v_mul_f32_e32 v141, v141, v146
	v_mfma_f32_16x16x32_bf16 v[146:149], v[60:63], v[16:19], 0
	s_nop 2
	v_mul_f32_e32 v136, 0xbe38aa3b, v136
	v_min_f32_e32 v136, 0x42e60000, v136
	v_exp_f32_e32 v136, v136
	v_mul_f32_e32 v137, 0xbe38aa3b, v137
	v_min_f32_e32 v137, 0x42e60000, v137
	v_exp_f32_e32 v137, v137
	v_add_f32_e32 v161, 1.0, v136
	v_rcp_f32_e32 v161, v161
	v_mul_f32_e32 v138, 0xbe38aa3b, v138
	v_min_f32_e32 v138, 0x42e60000, v138
	v_exp_f32_e32 v138, v138
	v_cndmask_b32_e32 v162, 0, v161, vcc
	v_mul_f32_e32 v136, v136, v161
	v_add_f32_e32 v161, 1.0, v137
	v_rcp_f32_e32 v161, v161
	v_cndmask_b32_e32 v136, 1.0, v136, vcc
	v_cmp_lt_i32_e32 vcc, v77, v98
	v_mul_f32_e32 v139, 0xbe38aa3b, v139
	v_mfma_f32_16x16x32_bf16 v[146:149], v[56:59], v[20:23], v[146:149]
	v_cndmask_b32_e32 v164, 0, v161, vcc
	v_mul_f32_e32 v137, v137, v161
	v_add_f32_e32 v161, 1.0, v138
	v_min_f32_e32 v139, 0x42e60000, v139
	v_rcp_f32_e32 v161, v161
	v_exp_f32_e32 v139, v139
	v_cndmask_b32_e32 v137, 1.0, v137, vcc
	v_cmp_lt_i32_e32 vcc, v78, v98
	v_mul_f32_e32 v146, 0xbe38aa3b, v146
	v_mul_f32_e32 v138, v138, v161
	v_cndmask_b32_e32 v165, 0, v161, vcc
	v_add_f32_e32 v161, 1.0, v139
	v_min_f32_e32 v146, 0x42e60000, v146
	v_rcp_f32_e32 v161, v161
	v_exp_f32_e32 v146, v146
	v_cndmask_b32_e32 v138, 1.0, v138, vcc
	v_cmp_lt_i32_e32 vcc, v79, v98
	v_mul_f32_e32 v147, 0xbe38aa3b, v147
	v_mul_f32_e32 v139, v139, v161
	v_cndmask_b32_e32 v166, 0, v161, vcc
	v_add_f32_e32 v161, 1.0, v146
	v_min_f32_e32 v147, 0x42e60000, v147
	v_rcp_f32_e32 v161, v161
	v_exp_f32_e32 v147, v147
	v_cndmask_b32_e32 v139, 1.0, v139, vcc
	v_cmp_lt_i32_e32 vcc, v154, v98
	v_mul_f32_e32 v148, 0xbe38aa3b, v148
	v_mul_f32_e32 v146, v146, v161
	v_cndmask_b32_e32 v167, 0, v161, vcc
	v_add_f32_e32 v161, 1.0, v147
	v_min_f32_e32 v148, 0x42e60000, v148
	v_mul_f32_e32 v149, 0xbe38aa3b, v149
	v_rcp_f32_e32 v161, v161
	v_exp_f32_e32 v148, v148
	v_min_f32_e32 v149, 0x42e60000, v149
	v_exp_f32_e32 v149, v149
	v_cndmask_b32_e32 v146, 1.0, v146, vcc
	v_cmp_lt_i32_e32 vcc, v155, v98
	v_mul_f32_e32 v147, v147, v161
	v_add_f32_e32 v170, 1.0, v149
	v_cndmask_b32_e32 v168, 0, v161, vcc
	v_add_f32_e32 v161, 1.0, v148
	v_rcp_f32_e32 v161, v161
	v_rcp_f32_e32 v170, v170
	v_cndmask_b32_e32 v147, 1.0, v147, vcc
	v_cmp_lt_i32_e32 vcc, v156, v98
	v_mul_f32_e32 v148, v148, v161
	v_mul_f32_e32 v149, v149, v170
	v_cndmask_b32_e32 v169, 0, v161, vcc
	v_cndmask_b32_e32 v148, 1.0, v148, vcc
	v_cmp_lt_i32_e32 vcc, v157, v98
	global_load_dwordx4 v[84:87], v[80:81], off
	s_nop 0
	global_load_dwordx4 v[80:83], v[82:83], off
	v_cndmask_b32_e32 v161, 1.0, v149, vcc
	v_cndmask_b32_e32 v98, 0, v170, vcc
	v_mul_f32_e32 v170, v161, v148
	v_mul_f32_e32 v171, v147, v170
	v_mul_f32_e32 v204, v146, v171
	v_mul_f32_e32 v205, v139, v204
	v_mul_f32_e32 v212, v138, v205
	v_mul_f32_e32 v213, v137, v212
	v_mul_f32_e32 v136, v136, v213
	ds_bpermute_b32 v137, v175, v136
	v_mul_f32_e32 v138, v163, v160
	v_mul_f32_e32 v139, v163, v159
	v_mul_f32_e32 v138, v150, v138
	v_mul_f32_e32 v139, v151, v139
	s_waitcnt lgkmcnt(0)
; __device__ __forceinline__ unsigned pk2(float lo, float hi) { return pg8::cvt_pk_bf16(lo, hi); }
; template <bool DIAG, int QT0>
; __device__ __forceinline__ void attn_group(const bf16x8 (&Kf)[2][2], const bf16x8 (&Vf)[4], const bf16x8 (&Qf)[4][2], f32x4 (&ot)[4][4], float (&carry)[4], int qb, int key0, int fr, int fq) {
;     ...
;         f32x4 s0 = (f32x4){0.f, 0.f, 0.f, 0.f}, s1 = (f32x4){0.f, 0.f, 0.f, 0.f};
; #pragma unroll
;         for (int ks = 0; ks < 2; ++ks) { s0 = __builtin_amdgcn_mfma_f32_16x16x32_bf16(Kf[0][ks], Qf[qt][ks], s0, 0, 0, 0); s1 = __builtin_amdgcn_mfma_f32_16x16x32_bf16(Kf[1][ks], Qf[qt][ks], s1, 0, 0, 0); }
;         const int qpos = qb * 64 + 16 * qt + fr, kpos0 = key0 + 8 * fq;
;         float be[8], om[8];
; #pragma unroll
;         for (int e = 0; e < 8; ++e) { const float s = (e < 4 ? s0[e & 3] : s1[e & 3]);
;             const float ez = __builtin_amdgcn_exp2f(fminf(s * (-0.125f * 1.4426950408889634f), 115.0f));
;             const float bt = __builtin_amdgcn_rcpf(1.0f + ez);
;             const bool valid = !DIAG || (kpos0 + e < qpos);
;             be[e] = valid ? bt : 0.f;
;             om[e] = valid ? ez * bt : 1.f; }
;         float ex[8], run = 1.f;
; #pragma unroll
;         for (int e = 7; e >= 0; --e) { ex[e] = run; run *= om[e]; }
;         const float T = run;
;         const float t1 = __shfl_down(T, 16); const float I1 = T * (fq < 3 ? t1 : 1.f);
;         const float t2 = __shfl_down(I1, 32); const float I2 = I1 * (fq < 2 ? t2 : 1.f);
;         const float xs = __shfl_down(I2, 16); const float X = (fq < 3 ? xs : 1.f);
;         const float TT = __shfl(I2, fr);
;         const float base = carry[qt] * X;
;         float p[8];
; #pragma unroll
;         for (int e = 0; e < 8; ++e) p[e] = be[e] * (base * ex[e]);
;         carry[qt] *= TT;
;         v4u pw; pw.x = pk2(p[0], p[1]); pw.y = pk2(p[2], p[3]); pw.z = pk2(p[4], p[5]); pw.w = pk2(p[6], p[7]);
;         Pf[qt] = __builtin_bit_cast(bf16x8, pw);
	v_cndmask_b32_e64 v137, v137, 1.0, s[2:3]
	v_mul_f32_e32 v137, v137, v136
	ds_bpermute_b32 v146, v181, v137
	v_mul_f32_e32 v136, v163, v158
	v_mul_f32_e32 v147, v152, v136
	v_mul_f32_e32 v148, v163, v153
	v_cvt_pk_bf16_f32 v136, v99, v141
	s_waitcnt lgkmcnt(0)
	v_cndmask_b32_e64 v99, 1.0, v146, s[4:5]
	v_mul_f32_e32 v158, v99, v137
	v_cvt_pk_bf16_f32 v137, v142, v145
	v_cvt_pk_bf16_f32 v138, v138, v139
	v_cvt_pk_bf16_f32 v139, v147, v148
	v_mfma_f32_16x16x32_bf16 v[146:149], v[52:55], v[0:3], 0
	ds_bpermute_b32 v99, v175, v158
	v_cmp_lt_i32_e32 vcc, v76, v96
	s_lshl_b32 s0, s18, 2
	v_mfma_f32_16x16x32_bf16 v[146:149], v[44:47], v[4:7], v[146:149]
	s_lshl_b32 s1, s12, 8
	s_waitcnt lgkmcnt(0)
	v_cndmask_b32_e64 v99, v99, 1.0, s[2:3]
	v_mul_f32_e32 v141, v99, v213
	v_mul_f32_e32 v141, v162, v141
	v_mfma_f32_16x16x32_bf16 v[150:153], v[60:63], v[0:3], 0
	s_nop 1
	v_mul_f32_e32 v146, 0xbe38aa3b, v146
	v_min_f32_e32 v146, 0x42e60000, v146
	v_exp_f32_e32 v146, v146
	v_mul_f32_e32 v147, 0xbe38aa3b, v147
	v_min_f32_e32 v147, 0x42e60000, v147
	v_exp_f32_e32 v147, v147
	v_add_f32_e32 v160, 1.0, v146
	v_rcp_f32_e32 v160, v160
	v_mul_f32_e32 v148, 0xbe38aa3b, v148
	v_min_f32_e32 v148, 0x42e60000, v148
	v_exp_f32_e32 v148, v148
	v_cndmask_b32_e32 v162, 0, v160, vcc
	v_mul_f32_e32 v146, v146, v160
	v_add_f32_e32 v160, 1.0, v147
	v_rcp_f32_e32 v160, v160
	v_cndmask_b32_e32 v146, 1.0, v146, vcc
	v_cmp_lt_i32_e32 vcc, v77, v96
	v_mul_f32_e32 v149, 0xbe38aa3b, v149
	v_mfma_f32_16x16x32_bf16 v[150:153], v[56:59], v[4:7], v[150:153]
	v_cndmask_b32_e32 v163, 0, v160, vcc
	v_mul_f32_e32 v147, v147, v160
	v_add_f32_e32 v160, 1.0, v148
	v_min_f32_e32 v149, 0x42e60000, v149
	v_rcp_f32_e32 v160, v160
	v_exp_f32_e32 v149, v149
	v_mul_f32_e32 v142, v99, v212
	v_cndmask_b32_e32 v147, 1.0, v147, vcc
	v_cmp_lt_i32_e32 vcc, v78, v96
	v_mul_f32_e32 v150, 0xbe38aa3b, v150
	v_mul_f32_e32 v142, v164, v142
	v_cndmask_b32_e32 v164, 0, v160, vcc
	v_mul_f32_e32 v148, v148, v160
	v_add_f32_e32 v160, 1.0, v149
	v_min_f32_e32 v150, 0x42e60000, v150
	v_rcp_f32_e32 v160, v160
	v_exp_f32_e32 v150, v150
	v_mul_f32_e32 v145, v99, v205
	v_cndmask_b32_e32 v148, 1.0, v148, vcc
	v_cmp_lt_i32_e32 vcc, v79, v96
	v_mul_f32_e32 v151, 0xbe38aa3b, v151
	v_mfma_f32_16x16x32_bf16 v[52:55], v[52:55], v[24:27], 0
	v_mul_f32_e32 v145, v165, v145
	v_cndmask_b32_e32 v165, 0, v160, vcc
	v_mul_f32_e32 v149, v149, v160
	v_add_f32_e32 v160, 1.0, v150
	v_min_f32_e32 v151, 0x42e60000, v151
	v_rcp_f32_e32 v160, v160
	v_exp_f32_e32 v151, v151
	v_mfma_f32_16x16x32_bf16 v[44:47], v[44:47], v[28:31], v[52:55]
	v_cndmask_b32_e32 v149, 1.0, v149, vcc
	v_cmp_lt_i32_e32 vcc, v154, v96
	v_mul_f32_e32 v152, 0xbe38aa3b, v152
	v_mul_f32_e32 v159, v99, v204
	v_cndmask_b32_e32 v204, 0, v160, vcc
	v_mul_f32_e32 v150, v150, v160
	v_add_f32_e32 v160, 1.0, v151
	v_min_f32_e32 v152, 0x42e60000, v152
	v_mul_f32_e32 v153, 0xbe38aa3b, v153
	v_rcp_f32_e32 v160, v160
	v_exp_f32_e32 v152, v152
	v_min_f32_e32 v153, 0x42e60000, v153
	v_exp_f32_e32 v153, v153
	v_mul_f32_e32 v44, 0xbe38aa3b, v44
	v_min_f32_e32 v44, 0x42e60000, v44
	v_cndmask_b32_e32 v150, 1.0, v150, vcc
	v_cmp_lt_i32_e32 vcc, v155, v96
	v_mfma_f32_16x16x32_bf16 v[60:63], v[60:63], v[24:27], 0
	v_exp_f32_e32 v44, v44
	v_cndmask_b32_e32 v205, 0, v160, vcc
	v_mul_f32_e32 v151, v151, v160
	v_add_f32_e32 v160, 1.0, v152
	v_rcp_f32_e32 v160, v160
	v_add_f32_e32 v213, 1.0, v153
	v_rcp_f32_e32 v213, v213
	v_mul_f32_e32 v45, 0xbe38aa3b, v45
	v_mfma_f32_16x16x32_bf16 v[52:55], v[56:59], v[28:31], v[60:63]
	v_add_f32_e32 v56, 1.0, v44
	v_min_f32_e32 v45, 0x42e60000, v45
	v_rcp_f32_e32 v56, v56
	v_exp_f32_e32 v45, v45
	v_cndmask_b32_e32 v151, 1.0, v151, vcc
	v_cmp_lt_i32_e32 vcc, v156, v96
	v_mul_f32_e32 v152, v152, v160
	v_mul_f32_e32 v153, v153, v213
	v_cndmask_b32_e32 v212, 0, v160, vcc
	v_cndmask_b32_e32 v152, 1.0, v152, vcc
	v_cmp_lt_i32_e32 vcc, v157, v96
	v_mul_f32_e32 v46, 0xbe38aa3b, v46
	v_mul_f32_e32 v44, v44, v56
	v_cndmask_b32_e32 v96, 0, v213, vcc
	v_cndmask_b32_e32 v153, 1.0, v153, vcc
	v_cmp_lt_i32_e32 vcc, v76, v97
	v_min_f32_e32 v46, 0x42e60000, v46
	v_exp_f32_e32 v46, v46
	v_cndmask_b32_e32 v57, 0, v56, vcc
	v_add_f32_e32 v56, 1.0, v45
	v_rcp_f32_e32 v56, v56
	v_cndmask_b32_e32 v44, 1.0, v44, vcc
	v_cmp_lt_i32_e32 vcc, v77, v97
	v_mul_f32_e32 v47, 0xbe38aa3b, v47
	v_mul_f32_e32 v45, v45, v56
	v_cndmask_b32_e32 v58, 0, v56, vcc
	v_add_f32_e32 v56, 1.0, v46
	v_min_f32_e32 v47, 0x42e60000, v47
	v_rcp_f32_e32 v56, v56
	v_exp_f32_e32 v47, v47
	v_cndmask_b32_e32 v45, 1.0, v45, vcc
	v_cmp_lt_i32_e32 vcc, v78, v97
	v_mul_f32_e32 v52, 0xbe38aa3b, v52
	v_mul_f32_e32 v46, v46, v56
	v_cndmask_b32_e32 v59, 0, v56, vcc
	v_add_f32_e32 v56, 1.0, v47
	v_min_f32_e32 v52, 0x42e60000, v52
	v_rcp_f32_e32 v56, v56
	v_exp_f32_e32 v52, v52
	v_cndmask_b32_e32 v46, 1.0, v46, vcc
	v_cmp_lt_i32_e32 vcc, v79, v97
	v_mul_f32_e32 v53, 0xbe38aa3b, v53
	v_mul_f32_e32 v47, v47, v56
	v_cndmask_b32_e32 v60, 0, v56, vcc
	v_add_f32_e32 v56, 1.0, v52
	v_min_f32_e32 v53, 0x42e60000, v53
	v_rcp_f32_e32 v56, v56
	v_exp_f32_e32 v53, v53
	v_cndmask_b32_e32 v47, 1.0, v47, vcc
	v_cmp_lt_i32_e32 vcc, v154, v97
	v_mul_f32_e32 v54, 0xbe38aa3b, v54
	v_mul_f32_e32 v52, v52, v56
	v_cndmask_b32_e32 v61, 0, v56, vcc
	v_add_f32_e32 v56, 1.0, v53
	v_min_f32_e32 v54, 0x42e60000, v54
	v_mul_f32_e32 v55, 0xbe38aa3b, v55
	v_rcp_f32_e32 v56, v56
	v_exp_f32_e32 v54, v54
	v_min_f32_e32 v55, 0x42e60000, v55
	v_exp_f32_e32 v55, v55
	v_mul_f32_e32 v152, v153, v152
	v_cndmask_b32_e32 v52, 1.0, v52, vcc
	v_cmp_lt_i32_e32 vcc, v155, v97
	v_mul_f32_e32 v151, v151, v152
	v_mul_f32_e32 v53, v53, v56
	v_cndmask_b32_e32 v62, 0, v56, vcc
	v_add_f32_e32 v56, 1.0, v54
	v_mul_f32_e32 v150, v150, v151
	v_rcp_f32_e32 v56, v56
	v_add_f32_e32 v76, 1.0, v55
	v_mul_f32_e32 v160, v149, v150
	v_rcp_f32_e32 v76, v76
	v_mul_f32_e32 v213, v148, v160
	v_mul_f32_e32 v214, v147, v213
	v_mul_f32_e32 v146, v146, v214
	v_cndmask_b32_e32 v53, 1.0, v53, vcc
	v_cmp_lt_i32_e32 vcc, v156, v97
	v_mul_f32_e32 v54, v54, v56
	ds_bpermute_b32 v147, v175, v146
	v_cndmask_b32_e32 v63, 0, v56, vcc
	v_cndmask_b32_e32 v54, 1.0, v54, vcc
	v_cmp_lt_i32_e32 vcc, v157, v97
	v_mul_f32_e32 v55, v55, v76
	s_waitcnt lgkmcnt(0)
; __device__ __forceinline__ unsigned pk2(float lo, float hi) { return pg8::cvt_pk_bf16(lo, hi); }
; template <bool DIAG, int QT0>
; __device__ __forceinline__ void attn_group(const bf16x8 (&Kf)[2][2], const bf16x8 (&Vf)[4], const bf16x8 (&Qf)[4][2], f32x4 (&ot)[4][4], float (&carry)[4], int qb, int key0, int fr, int fq) {
;     ...
;         float ex[8], run = 1.f;
; #pragma unroll
;         for (int e = 7; e >= 0; --e) { ex[e] = run; run *= om[e]; }
;         const float T = run;
;         const float t1 = __shfl_down(T, 16); const float I1 = T * (fq < 3 ? t1 : 1.f);
;         const float t2 = __shfl_down(I1, 32); const float I2 = I1 * (fq < 2 ? t2 : 1.f);
;         const float xs = __shfl_down(I2, 16); const float X = (fq < 3 ? xs : 1.f);
;         const float TT = __shfl(I2, fr);
;         const float base = carry[qt] * X;
;         float p[8];
; #pragma unroll
;         for (int e = 0; e < 8; ++e) p[e] = be[e] * (base * ex[e]);
;         carry[qt] *= TT;
;         v4u pw; pw.x = pk2(p[0], p[1]); pw.y = pk2(p[2], p[3]); pw.z = pk2(p[4], p[5]); pw.w = pk2(p[6], p[7]);
;         Pf[qt] = __builtin_bit_cast(bf16x8, pw);
;     }
; #pragma unroll
;     for (int dt = 0; dt < 4; ++dt)
; #pragma unroll
;         for (int qt = QT0; qt < 4; ++qt) if (live[qt]) ot[dt][qt] = __builtin_amdgcn_mfma_f32_16x16x32_bf16(Vf[dt], Pf[qt], ot[dt][qt], 0, 0, 0);
; }
; __device__ __forceinline__ void attn_unit(const bf16* __restrict__ U, const bf16* __restrict__ VT, bf16* __restrict__ Y, int b, int qb, LAS float* red, int wave, int lane) {
;     ...
;     take(); fetch(2 * qb);     attn_group<true, 2>(Kf, Vf, Qf, ot, carry, qb, (2 * qb + 1) * 32, fr, fq);
;     take(); fetch(2 * qb - 1); attn_group<true, 0>(Kf, Vf, Qf, ot, carry, qb, (2 * qb) * 32, fr, fq);
	v_cndmask_b32_e64 v147, v147, 1.0, s[2:3]
	v_cndmask_b32_e32 v55, 1.0, v55, vcc
	v_mul_f32_e32 v54, v55, v54
	v_mul_f32_e32 v53, v53, v54
	v_mul_f32_e32 v52, v52, v53
	v_mul_f32_e32 v47, v47, v52
	v_mul_f32_e32 v146, v147, v146
	v_mul_f32_e32 v46, v46, v47
	ds_bpermute_b32 v147, v181, v146
	v_mul_f32_e32 v45, v45, v46
	v_mul_f32_e32 v44, v44, v45
	v_cndmask_b32_e32 v56, 0, v76, vcc
	ds_bpermute_b32 v76, v175, v44
	v_mul_f32_e32 v148, v166, v159
	v_mul_f32_e32 v149, v99, v171
	v_mul_f32_e32 v159, v99, v170
	v_mul_f32_e32 v161, v99, v161
	v_mul_f32_e32 v98, v99, v98
	s_waitcnt lgkmcnt(1)
	v_cndmask_b32_e64 v99, 1.0, v147, s[4:5]
	v_mul_f32_e32 v166, v99, v146
	ds_bpermute_b32 v99, v175, v166
	s_waitcnt lgkmcnt(1)
	v_cndmask_b32_e64 v76, v76, 1.0, s[2:3]
	v_mul_f32_e32 v44, v76, v44
	ds_bpermute_b32 v76, v181, v44
	v_mul_f32_e32 v149, v167, v149
	v_mul_f32_e32 v159, v168, v159
	v_mul_f32_e32 v161, v169, v161
	v_cvt_pk_bf16_f32 v146, v141, v142
	v_cvt_pk_bf16_f32 v147, v145, v148
	v_cvt_pk_bf16_f32 v148, v149, v159
	v_cvt_pk_bf16_f32 v149, v161, v98
	s_waitcnt lgkmcnt(1)
	v_cndmask_b32_e64 v98, v99, 1.0, s[2:3]
	v_mul_f32_e32 v98, v98, v140
	v_mul_f32_e32 v145, v98, v150
	s_waitcnt lgkmcnt(0)
	v_cndmask_b32_e64 v76, 1.0, v76, s[4:5]
	v_mul_f32_e32 v77, v165, v145
	v_mul_f32_e32 v145, v76, v44
	ds_bpermute_b32 v44, v175, v145
	v_mul_f32_e32 v141, v98, v213
	v_mul_f32_e32 v142, v98, v160
	v_mul_f32_e32 v99, v98, v214
	v_mul_f32_e32 v141, v163, v141
	s_waitcnt lgkmcnt(0)
	v_cndmask_b32_e64 v44, v44, 1.0, s[2:3]
	v_mul_f32_e32 v142, v164, v142
	v_mul_f32_e32 v44, v44, v143
	v_mul_f32_e32 v99, v162, v99
	v_mul_f32_e32 v78, v98, v151
	v_mul_f32_e32 v79, v98, v152
	v_mul_f32_e32 v97, v98, v153
	v_cvt_pk_bf16_f32 v150, v99, v141
	v_cvt_pk_bf16_f32 v151, v142, v77
	v_mul_f32_e32 v45, v44, v45
	v_mul_f32_e32 v46, v44, v46
	v_mul_f32_e32 v47, v44, v47
	v_mul_f32_e32 v52, v44, v52
	v_mul_f32_e32 v53, v44, v53
	v_mul_f32_e32 v54, v44, v54
	v_mul_f32_e32 v55, v44, v55
	ds_bpermute_b32 v142, v183, v166
	ds_bpermute_b32 v141, v183, v145
	v_mul_f32_e32 v78, v204, v78
	v_mul_f32_e32 v79, v205, v79
	v_mul_f32_e32 v97, v212, v97
	v_mul_f32_e32 v96, v98, v96
	v_mul_f32_e32 v45, v57, v45
	v_mul_f32_e32 v46, v58, v46
	v_mul_f32_e32 v47, v59, v47
	v_mul_f32_e32 v52, v60, v52
	v_mul_f32_e32 v53, v61, v53
	v_mul_f32_e32 v54, v62, v54
	v_mul_f32_e32 v55, v63, v55
	v_mul_f32_e32 v44, v44, v56
	ds_bpermute_b32 v212, v183, v144
	ds_bpermute_b32 v213, v183, v158
	v_cvt_pk_bf16_f32 v152, v78, v79
	v_cvt_pk_bf16_f32 v153, v97, v96
	s_waitcnt vmcnt(11)
	v_mfma_f32_16x16x32_bf16 v[96:99], v[40:43], v[136:139], 0
	v_cvt_pk_bf16_f32 v154, v45, v46
	v_cvt_pk_bf16_f32 v155, v47, v52
	v_cvt_pk_bf16_f32 v156, v53, v54
	v_mfma_f32_16x16x32_bf16 v[76:79], v[40:43], v[146:149], 0
	v_cvt_pk_bf16_f32 v157, v55, v44
	s_sub_i32 s0, s0, s1
	s_waitcnt lgkmcnt(2)
	v_pk_mul_f32 v[204:205], v[140:141], v[142:143]
	v_mfma_f32_16x16x32_bf16 v[60:63], v[40:43], v[150:153], v[72:75]
	s_add_i32 s15, s0, -2
	v_mfma_f32_16x16x32_bf16 v[44:47], v[40:43], v[154:157], v[100:103]
	s_waitcnt vmcnt(10)
	v_mfma_f32_16x16x32_bf16 v[100:103], v[36:39], v[136:139], 0
	v_mfma_f32_16x16x32_bf16 v[72:75], v[36:39], v[146:149], 0
	v_mfma_f32_16x16x32_bf16 v[56:59], v[36:39], v[150:153], v[68:71]
	v_mfma_f32_16x16x32_bf16 v[40:43], v[36:39], v[154:157], v[92:95]
	s_waitcnt vmcnt(9)
	v_mfma_f32_16x16x32_bf16 v[92:95], v[48:51], v[136:139], 0
	v_mfma_f32_16x16x32_bf16 v[68:71], v[48:51], v[146:149], 0
	v_mfma_f32_16x16x32_bf16 v[52:55], v[48:51], v[150:153], v[64:67]
	v_mfma_f32_16x16x32_bf16 v[36:39], v[48:51], v[154:157], v[88:91]
	s_waitcnt vmcnt(8)
	v_mfma_f32_16x16x32_bf16 v[88:91], v[32:35], v[136:139], 0
	v_mfma_f32_16x16x32_bf16 v[64:67], v[32:35], v[146:149], 0
	v_mfma_f32_16x16x32_bf16 v[48:51], v[32:35], v[150:153], v[132:135]
	v_mfma_f32_16x16x32_bf16 v[32:35], v[32:35], v[154:157], v[128:131]
	s_add_i32 s0, s15, 1
	s_cmp_lt_i32 s0, 0
	s_cbranch_scc1 .LBB0_222
